# attention combine: 16-lane sum of squares via four DPP adds instead of four ds_bpermute round trips per row group
# baseline (speedup 1.0000x reference)
; __device__ __forceinline__ float bf_lo(unsigned w) { return __uint_as_float(w << 16); }
; __device__ __forceinline__ float bf_hi(unsigned w) { return __uint_as_float(w & 0xffff0000u); }
; __global__ void __launch_bounds__(NWAVES * 64, 2) trunk_fwd(Args args) {
;     ...
;                     { int lane_ = threadIdx.x & 63; asm volatile("" : "+v"(lane_));
;                       const float lam = LAM[li], post = 1.0f - (li == 0 ? LAMBDA_INIT0 : LAMBDA_INIT2);
;                       const f32x4* gp = (const f32x4*)(ARGIN(I_SUBLN) + li * 128 + (lane_ & 15) * 8); const f32x4 ga = gp[0], gb = gp[1];
;                       const size_t rowbase = (size_t)b * SEQ + (size_t)qb * 256 + wid * 32 + (lane_ >> 4); const int cofs = h * 128 + (lane_ & 15) * 8;
;                       v4u aa[8], cc[8];
; #pragma unroll
;                       for (int it = 0; it < 8; ++it) { const size_t row = rowbase + it * 4; aa[it] = *(const v4u*)(ORAW + row * 1024 + cofs); cc[it] = *(const v4u*)(ORAW + row * 1024 + 512 + cofs); }
; #pragma unroll
;                       for (int it = 0; it < 8; ++it) { const size_t row = rowbase + it * 4; const v4u a = aa[it], c = cc[it];
;                         float v[8] = {bf_lo(a.x) - lam * bf_lo(c.x), bf_hi(a.x) - lam * bf_hi(c.x), bf_lo(a.y) - lam * bf_lo(c.y), bf_hi(a.y) - lam * bf_hi(c.y),
;                                       bf_lo(a.z) - lam * bf_lo(c.z), bf_hi(a.z) - lam * bf_hi(c.z), bf_lo(a.w) - lam * bf_lo(c.w), bf_hi(a.w) - lam * bf_hi(c.w)};
;                         float sv = 0.f;
; #pragma unroll
;                         for (int e = 0; e < 8; ++e) sv += v[e] * v[e];
;                         sv += __shfl_xor(sv, 1); sv += __shfl_xor(sv, 2); sv += __shfl_xor(sv, 4); sv += __shfl_xor(sv, 8);
;                         const float r = __builtin_amdgcn_rsqf(sv * (1.0f / 128.0f) + EPS) * post;
.LBB0_363:
	v_and_b32_e32 v0, 63, v206
	s_barrier
	s_load_dwordx2 s[6:7], s[62:63], 0x70
	v_lshlrev_b32_e32 v2, 3, v0
	v_and_b32_e32 v4, 0x78, v2
	v_ashrrev_i32_e32 v2, 4, v0
	v_ashrrev_i32_e32 v3, 31, v2
	s_waitcnt lgkmcnt(0)
	s_add_u32 s6, s6, s74
	s_addc_u32 s7, s7, s75
	s_add_u32 s8, s43, s67
	s_addc_u32 s9, s44, s4
	v_lshl_add_u64 v[2:3], s[8:9], 0, v[2:3]
	v_or_b32_e32 v0, s65, v4
	v_lshlrev_b64 v[54:55], 11, v[2:3]
	v_lshl_add_u64 v[2:3], s[70:71], 0, v[54:55]
	v_lshlrev_b32_e32 v0, 1, v0
	v_lshl_add_u64 v[10:11], v[2:3], 0, v[0:1]
	global_load_dwordx4 v[12:15], v[10:11], off
	global_load_dwordx4 v[58:61], v[10:11], off offset:1024
	global_load_dword v56, v1, s[72:73]
	v_and_b32_e32 v3, 64, v246
	v_xor_b32_e32 v2, 1, v246
	v_add_u32_e32 v80, 64, v3
	v_cmp_lt_i32_e32 vcc, v2, v80
	s_movk_i32 s8, 0x2000
	v_lshlrev_b32_e32 v6, 2, v4
	v_cndmask_b32_e32 v2, v246, v2, vcc
	v_add_co_u32_e32 v18, vcc, s8, v10
	v_lshlrev_b32_e32 v57, 2, v2
	global_load_dwordx4 v[2:5], v6, s[6:7] offset:16
	s_nop 0
	global_load_dwordx4 v[6:9], v6, s[6:7]
	s_mov_b64 s[6:7], 0x2000
	v_addc_co_u32_e32 v19, vcc, 0, v11, vcc
	v_lshl_add_u64 v[16:17], v[10:11], 0, s[6:7]
	global_load_dwordx4 v[62:65], v[18:19], off
	global_load_dwordx4 v[66:69], v[16:17], off offset:1024
	s_movk_i32 s9, 0x4000
	v_add_co_u32_e32 v22, vcc, s9, v10
	s_movk_i32 s12, 0x6000
	s_nop 0
	v_addc_co_u32_e32 v23, vcc, 0, v11, vcc
	v_add_co_u32_e32 v26, vcc, s12, v10
	s_mov_b32 s20, 0x8000
	s_nop 0
	v_addc_co_u32_e32 v27, vcc, 0, v11, vcc
	v_add_co_u32_e32 v30, vcc, s20, v10
	s_mov_b64 s[6:7], 0x4000
	s_nop 0
	v_addc_co_u32_e32 v31, vcc, 0, v11, vcc
	s_mov_b32 s26, 0xa000
	v_lshl_add_u64 v[20:21], v[10:11], 0, s[6:7]
	s_mov_b64 s[6:7], 0x6000
	v_add_co_u32_e32 v74, vcc, s26, v10
	v_lshl_add_u64 v[24:25], v[10:11], 0, s[6:7]
	s_mov_b64 s[6:7], 0x8000
	v_addc_co_u32_e32 v75, vcc, 0, v11, vcc
	s_mov_b32 s27, 0xc000
	v_lshl_add_u64 v[28:29], v[10:11], 0, s[6:7]
	s_mov_b64 s[6:7], 0xa000
	v_add_co_u32_e32 v16, vcc, s27, v10
	v_lshl_add_u64 v[32:33], v[10:11], 0, s[6:7]
	s_mov_b64 s[6:7], 0xc000
	v_addc_co_u32_e32 v17, vcc, 0, v11, vcc
	v_lshl_add_u64 v[76:77], v[10:11], 0, s[6:7]
	global_load_dwordx4 v[50:53], v[22:23], off
	global_load_dwordx4 v[70:73], v[20:21], off offset:1024
	global_load_dwordx4 v[42:45], v[26:27], off
	global_load_dwordx4 v[46:49], v[24:25], off offset:1024
	global_load_dwordx4 v[34:37], v[30:31], off
	global_load_dwordx4 v[38:41], v[28:29], off offset:1024
	s_nop 0
	global_load_dwordx4 v[26:29], v[74:75], off
	s_nop 0
	global_load_dwordx4 v[30:33], v[32:33], off offset:1024
	s_nop 0
	global_load_dwordx4 v[18:21], v[16:17], off
	global_load_dwordx4 v[22:25], v[76:77], off offset:1024
	s_mov_b64 s[6:7], 0xe000
	s_mov_b32 s1, 0xe000
	v_lshl_add_u64 v[78:79], v[10:11], 0, s[6:7]
	s_add_i32 s42, s42, 1
	s_movk_i32 s33, 0x2000
	s_movk_i32 s2, 0x6000
	s_cmp_eq_u32 s42, 4
	s_waitcnt vmcnt(16)
	v_lshlrev_b32_e32 v16, 16, v12
	s_waitcnt vmcnt(15)
	v_lshlrev_b32_e32 v17, 16, v58
	v_and_b32_e32 v12, 0xffff0000, v12
	v_and_b32_e32 v58, 0xffff0000, v58
	v_lshlrev_b32_e32 v74, 16, v13
	v_lshlrev_b32_e32 v75, 16, v59
	v_and_b32_e32 v13, 0xffff0000, v13
	v_and_b32_e32 v59, 0xffff0000, v59
	s_waitcnt vmcnt(14)
	v_fma_f32 v84, -v56, v58, v12
	v_fma_f32 v86, -v56, v59, v13
	v_and_b32_e32 v12, 0xffff0000, v15
	v_and_b32_e32 v13, 0xffff0000, v61
	v_lshlrev_b32_e32 v82, 16, v61
	v_fma_f32 v83, -v56, v17, v16
	v_fma_f32 v61, -v56, v13, v12
	v_mul_f32_e32 v12, v84, v84
	v_fma_f32 v85, -v56, v75, v74
	v_fmac_f32_e32 v12, v83, v83
	v_lshlrev_b32_e32 v76, 16, v14
	v_lshlrev_b32_e32 v77, 16, v60
	v_fmac_f32_e32 v12, v85, v85
	v_and_b32_e32 v14, 0xffff0000, v14
	v_and_b32_e32 v60, 0xffff0000, v60
	v_fma_f32 v76, -v56, v77, v76
	v_fmac_f32_e32 v12, v86, v86
	v_lshlrev_b32_e32 v81, 16, v15
	v_fma_f32 v77, -v56, v60, v14
	v_fmac_f32_e32 v12, v76, v76
	v_fma_f32 v81, -v56, v82, v81
	v_fmac_f32_e32 v12, v77, v77
	v_fmac_f32_e32 v12, v81, v81
	v_fmac_f32_e32 v12, v61, v61
	v_xor_b32_e32 v14, 2, v246
	v_cmp_lt_i32_e32 vcc, v14, v80
	v_lshl_add_u64 v[74:75], s[50:51], 0, v[0:1]
	s_waitcnt vmcnt(10)
	v_lshlrev_b32_e32 v82, 16, v66
	v_cndmask_b32_e32 v14, v246, v14, vcc
	v_lshlrev_b32_e32 v58, 2, v14
	s_waitcnt lgkmcnt(0)
	s_nop 1
	v_add_f32_dpp v12, v12, v12 quad_perm:[1,0,3,2] row_mask:0xf bank_mask:0xf
	v_xor_b32_e32 v14, 4, v246
	v_cmp_lt_i32_e32 vcc, v14, v80
	v_and_b32_e32 v66, 0xffff0000, v66
	v_lshl_add_u64 v[54:55], v[74:75], 0, v[54:55]
	v_cndmask_b32_e32 v14, v246, v14, vcc
	v_lshlrev_b32_e32 v59, 2, v14
	s_waitcnt lgkmcnt(0)
	s_nop 1
	v_add_f32_dpp v12, v12, v12 quad_perm:[2,3,0,1] row_mask:0xf bank_mask:0xf
	v_xor_b32_e32 v14, 8, v246
	v_cmp_lt_i32_e32 vcc, v14, v80
	s_waitcnt lgkmcnt(0)
	s_nop 1
	v_add_f32_dpp v12, v12, v12 row_half_mirror row_mask:0xf bank_mask:0xf
	v_cndmask_b32_e32 v14, v246, v14, vcc
	v_lshlrev_b32_e32 v60, 2, v14
	v_add_co_u32_e32 v10, vcc, s1, v10
	s_mov_b32 s1, 0xa000
	s_nop 0
	v_addc_co_u32_e32 v11, vcc, 0, v11, vcc
	s_waitcnt lgkmcnt(0)
; __device__ __forceinline__ float bf_lo(unsigned w) { return __uint_as_float(w << 16); }
; __device__ __forceinline__ float bf_hi(unsigned w) { return __uint_as_float(w & 0xffff0000u); }
; __device__ __forceinline__ unsigned pk2(float lo, float hi) { return pg8::cvt_pk_bf16(lo, hi); }
; __global__ void __launch_bounds__(NWAVES * 64, 2) trunk_fwd(Args args) {
;     ...
;                       for (int it = 0; it < 8; ++it) { const size_t row = rowbase + it * 4; const v4u a = aa[it], c = cc[it];
;                         float v[8] = {bf_lo(a.x) - lam * bf_lo(c.x), bf_hi(a.x) - lam * bf_hi(c.x), bf_lo(a.y) - lam * bf_lo(c.y), bf_hi(a.y) - lam * bf_hi(c.y),
;                                       bf_lo(a.z) - lam * bf_lo(c.z), bf_hi(a.z) - lam * bf_hi(c.z), bf_lo(a.w) - lam * bf_lo(c.w), bf_hi(a.w) - lam * bf_hi(c.w)};
;                         float sv = 0.f;
; #pragma unroll
;                         for (int e = 0; e < 8; ++e) sv += v[e] * v[e];
;                         sv += __shfl_xor(sv, 1); sv += __shfl_xor(sv, 2); sv += __shfl_xor(sv, 4); sv += __shfl_xor(sv, 8);
;                         const float r = __builtin_amdgcn_rsqf(sv * (1.0f / 128.0f) + EPS) * post;
;                         v4u o; o.x = pk2(v[0] * r * ga[0], v[1] * r * ga[1]); o.y = pk2(v[2] * r * ga[2], v[3] * r * ga[3]); o.z = pk2(v[4] * r * gb[0], v[5] * r * gb[1]); o.w = pk2(v[6] * r * gb[2], v[7] * r * gb[3]);
;                         *(v4u*)(MIX + row * 1024 + cofs) = o; }
	s_nop 1
	v_add_f32_dpp v12, v12, v12 row_mirror row_mask:0xf bank_mask:0xf
	v_fmamk_f32 v12, v12, 0x3c000000, v207
	v_rsq_f32_e32 v80, v12
	global_load_dwordx4 v[10:13], v[10:11], off
	s_nop 0
	global_load_dwordx4 v[14:17], v[78:79], off offset:1024
	v_mul_f32_e32 v0, v219, v80
	v_lshlrev_b32_e32 v80, 16, v62
	v_and_b32_e32 v62, 0xffff0000, v62
	v_fma_f32 v80, -v56, v82, v80
	v_fma_f32 v66, -v56, v66, v62
	v_lshlrev_b32_e32 v62, 16, v63
	v_lshlrev_b32_e32 v82, 16, v67
	v_fma_f32 v82, -v56, v82, v62
	v_and_b32_e32 v62, 0xffff0000, v63
	v_and_b32_e32 v63, 0xffff0000, v67
	v_fma_f32 v67, -v56, v63, v62
	v_lshlrev_b32_e32 v62, 16, v64
	v_lshlrev_b32_e32 v63, 16, v68
	v_mul_f32_e32 v78, v83, v0
	v_fma_f32 v83, -v56, v63, v62
	v_and_b32_e32 v62, 0xffff0000, v64
	v_and_b32_e32 v63, 0xffff0000, v68
	v_fma_f32 v68, -v56, v63, v62
	v_lshlrev_b32_e32 v62, 16, v65
	v_lshlrev_b32_e32 v63, 16, v69
	v_mul_f32_e32 v79, v84, v0
	v_fma_f32 v84, -v56, v63, v62
	v_and_b32_e32 v62, 0xffff0000, v65
	v_and_b32_e32 v63, 0xffff0000, v69
	v_fma_f32 v69, -v56, v63, v62
	v_mul_f32_e32 v63, v66, v66
	v_fmac_f32_e32 v63, v80, v80
	v_fmac_f32_e32 v63, v82, v82
	v_fmac_f32_e32 v63, v67, v67
	v_fmac_f32_e32 v63, v83, v83
	v_fmac_f32_e32 v63, v68, v68
	v_fmac_f32_e32 v63, v84, v84
	v_fmac_f32_e32 v63, v69, v69
	v_mul_f32_e32 v78, v6, v78
	v_mul_f32_e32 v62, v7, v79
	v_cvt_pk_bf16_f32 v62, v78, v62
	v_mul_f32_e32 v65, v85, v0
	s_waitcnt lgkmcnt(0)
	s_nop 1
	v_add_f32_dpp v64, v63, v63 quad_perm:[1,0,3,2] row_mask:0xf bank_mask:0xf
	v_mul_f32_e32 v63, v86, v0
	v_mul_f32_e32 v65, v8, v65
	v_mul_f32_e32 v63, v9, v63
	v_cvt_pk_bf16_f32 v63, v65, v63
	v_mul_f32_e32 v65, v76, v0
	s_waitcnt lgkmcnt(0)
	s_nop 1
	v_add_f32_dpp v76, v64, v64 quad_perm:[2,3,0,1] row_mask:0xf bank_mask:0xf
	v_mul_f32_e32 v64, v2, v65
	v_mul_f32_e32 v65, v77, v0
	v_mul_f32_e32 v65, v3, v65
	v_cvt_pk_bf16_f32 v64, v64, v65
	s_waitcnt lgkmcnt(0)
	s_nop 1
	v_add_f32_dpp v65, v76, v76 row_half_mirror row_mask:0xf bank_mask:0xf
	v_mul_f32_e32 v77, v81, v0
	v_mul_f32_e32 v0, v61, v0
	v_mul_f32_e32 v77, v4, v77
	v_mul_f32_e32 v0, v5, v0
	s_waitcnt lgkmcnt(0)
	s_nop 1
	v_add_f32_dpp v61, v65, v65 row_mirror row_mask:0xf bank_mask:0xf
	v_fmamk_f32 v61, v61, 0x3c000000, v207
	v_rsq_f32_e32 v61, v61
	v_cvt_pk_bf16_f32 v65, v77, v0
	global_store_dwordx4 v[54:55], v[62:65], off
	v_mul_f32_e32 v0, v219, v61
	s_waitcnt vmcnt(12)
	v_lshlrev_b32_e32 v63, 16, v50
	s_waitcnt vmcnt(11)
	v_lshlrev_b32_e32 v64, 16, v70
	v_fma_f32 v64, -v56, v64, v63
	v_and_b32_e32 v50, 0xffff0000, v50
	v_and_b32_e32 v63, 0xffff0000, v70
	v_fma_f32 v65, -v56, v63, v50
	v_lshlrev_b32_e32 v50, 16, v51
	v_lshlrev_b32_e32 v63, 16, v71
	v_mul_f32_e32 v62, v66, v0
	v_fma_f32 v66, -v56, v63, v50
	v_and_b32_e32 v50, 0xffff0000, v51
	v_and_b32_e32 v51, 0xffff0000, v71
	v_fma_f32 v70, -v56, v51, v50
	v_lshlrev_b32_e32 v50, 16, v52
	v_lshlrev_b32_e32 v51, 16, v72
	v_fma_f32 v71, -v56, v51, v50
	v_and_b32_e32 v50, 0xffff0000, v52
	v_and_b32_e32 v51, 0xffff0000, v72
	v_fma_f32 v72, -v56, v51, v50
	v_lshlrev_b32_e32 v50, 16, v53
	v_lshlrev_b32_e32 v51, 16, v73
	v_fma_f32 v74, -v56, v51, v50
	v_and_b32_e32 v50, 0xffff0000, v53
	v_and_b32_e32 v51, 0xffff0000, v73
	v_fma_f32 v73, -v56, v51, v50
	v_mul_f32_e32 v51, v65, v65
	v_fmac_f32_e32 v51, v64, v64
	v_fmac_f32_e32 v51, v66, v66
	v_fmac_f32_e32 v51, v70, v70
	v_fmac_f32_e32 v51, v71, v71
	v_fmac_f32_e32 v51, v72, v72
	v_fmac_f32_e32 v51, v74, v74
	v_fmac_f32_e32 v51, v73, v73
	v_mul_f32_e32 v61, v80, v0
	v_mul_f32_e32 v62, v7, v62
	v_mul_f32_e32 v61, v6, v61
	v_cvt_pk_bf16_f32 v50, v61, v62
	s_waitcnt lgkmcnt(0)
	s_nop 1
	v_add_f32_dpp v52, v51, v51 quad_perm:[1,0,3,2] row_mask:0xf bank_mask:0xf
	v_mul_f32_e32 v61, v67, v0
	v_mul_f32_e32 v51, v9, v61
	v_mul_f32_e32 v53, v82, v0
	v_mul_f32_e32 v53, v8, v53
	s_waitcnt lgkmcnt(0)
	s_nop 1
	v_add_f32_dpp v61, v52, v52 quad_perm:[2,3,0,1] row_mask:0xf bank_mask:0xf
	v_cvt_pk_bf16_f32 v51, v53, v51
	v_mul_f32_e32 v53, v83, v0
	v_mul_f32_e32 v52, v68, v0
	v_mul_f32_e32 v53, v2, v53
	s_waitcnt lgkmcnt(0)
	s_nop 1
	v_add_f32_dpp v61, v61, v61 row_half_mirror row_mask:0xf bank_mask:0xf
	v_mul_f32_e32 v52, v3, v52
	v_cvt_pk_bf16_f32 v52, v53, v52
	v_mul_f32_e32 v53, v84, v0
	v_mul_f32_e32 v0, v69, v0
	v_mul_f32_e32 v53, v4, v53
	v_mul_f32_e32 v0, v5, v0
	v_cvt_pk_bf16_f32 v53, v53, v0
	s_waitcnt lgkmcnt(0)
	s_nop 1
	v_add_f32_dpp v0, v61, v61 row_mirror row_mask:0xf bank_mask:0xf
	v_add_co_u32_e32 v62, vcc, s8, v54
	v_fmamk_f32 v0, v0, 0x3c000000, v207
	s_nop 0
	v_addc_co_u32_e32 v63, vcc, 0, v55, vcc
	global_store_dwordx4 v[62:63], v[50:53], off
	v_rsq_f32_e32 v0, v0
	s_waitcnt vmcnt(11)
	v_lshlrev_b32_e32 v52, 16, v42
	s_waitcnt vmcnt(10)
	v_lshlrev_b32_e32 v53, 16, v46
	v_and_b32_e32 v42, 0xffff0000, v42
	v_and_b32_e32 v46, 0xffff0000, v46
	v_fma_f32 v52, -v56, v53, v52
	v_fma_f32 v53, -v56, v46, v42
	v_lshlrev_b32_e32 v42, 16, v43
	v_lshlrev_b32_e32 v46, 16, v47
	v_fma_f32 v61, -v56, v46, v42
	v_and_b32_e32 v42, 0xffff0000, v43
	v_and_b32_e32 v43, 0xffff0000, v47
	v_fma_f32 v62, -v56, v43, v42
	v_lshlrev_b32_e32 v42, 16, v44
	v_lshlrev_b32_e32 v43, 16, v48
	v_fma_f32 v63, -v56, v43, v42
	v_and_b32_e32 v42, 0xffff0000, v44
	v_and_b32_e32 v43, 0xffff0000, v48
	v_mul_f32_e32 v0, v219, v0
	v_fma_f32 v48, -v56, v43, v42
	v_lshlrev_b32_e32 v42, 16, v45
	v_lshlrev_b32_e32 v43, 16, v49
	v_mul_f32_e32 v50, v64, v0
	v_fma_f32 v64, -v56, v43, v42
	v_and_b32_e32 v42, 0xffff0000, v45
	v_and_b32_e32 v43, 0xffff0000, v49
	v_fma_f32 v49, -v56, v43, v42
	v_mul_f32_e32 v43, v53, v53
	v_fmac_f32_e32 v43, v52, v52
	v_fmac_f32_e32 v43, v61, v61
	v_fmac_f32_e32 v43, v62, v62
	v_fmac_f32_e32 v43, v63, v63
	v_fmac_f32_e32 v43, v48, v48
	v_fmac_f32_e32 v43, v64, v64
	v_fmac_f32_e32 v43, v49, v49
	v_mul_f32_e32 v46, v70, v0
	v_mul_f32_e32 v45, v66, v0
	v_mul_f32_e32 v51, v65, v0
	v_mul_f32_e32 v45, v8, v45
	s_waitcnt lgkmcnt(0)
; __device__ __forceinline__ float bf_lo(unsigned w) { return __uint_as_float(w << 16); }
; __device__ __forceinline__ float bf_hi(unsigned w) { return __uint_as_float(w & 0xffff0000u); }
; __device__ __forceinline__ unsigned pk2(float lo, float hi) { return pg8::cvt_pk_bf16(lo, hi); }
; __global__ void __launch_bounds__(NWAVES * 64, 2) trunk_fwd(Args args) {
;     ...
;                       for (int it = 0; it < 8; ++it) { const size_t row = rowbase + it * 4; const v4u a = aa[it], c = cc[it];
;                         float v[8] = {bf_lo(a.x) - lam * bf_lo(c.x), bf_hi(a.x) - lam * bf_hi(c.x), bf_lo(a.y) - lam * bf_lo(c.y), bf_hi(a.y) - lam * bf_hi(c.y),
;                                       bf_lo(a.z) - lam * bf_lo(c.z), bf_hi(a.z) - lam * bf_hi(c.z), bf_lo(a.w) - lam * bf_lo(c.w), bf_hi(a.w) - lam * bf_hi(c.w)};
;                         float sv = 0.f;
; #pragma unroll
;                         for (int e = 0; e < 8; ++e) sv += v[e] * v[e];
;                         sv += __shfl_xor(sv, 1); sv += __shfl_xor(sv, 2); sv += __shfl_xor(sv, 4); sv += __shfl_xor(sv, 8);
;                         const float r = __builtin_amdgcn_rsqf(sv * (1.0f / 128.0f) + EPS) * post;
;                         v4u o; o.x = pk2(v[0] * r * ga[0], v[1] * r * ga[1]); o.y = pk2(v[2] * r * ga[2], v[3] * r * ga[3]); o.z = pk2(v[4] * r * gb[0], v[5] * r * gb[1]); o.w = pk2(v[6] * r * gb[2], v[7] * r * gb[3]);
;                         *(v4u*)(MIX + row * 1024 + cofs) = o; }
	s_nop 1
	v_add_f32_dpp v44, v43, v43 quad_perm:[1,0,3,2] row_mask:0xf bank_mask:0xf
	v_mul_f32_e32 v43, v9, v46
	v_mul_f32_e32 v50, v6, v50
	v_mul_f32_e32 v51, v7, v51
	v_cvt_pk_bf16_f32 v42, v50, v51
	s_waitcnt lgkmcnt(0)
	s_nop 1
	v_add_f32_dpp v46, v44, v44 quad_perm:[2,3,0,1] row_mask:0xf bank_mask:0xf
	v_cvt_pk_bf16_f32 v43, v45, v43
	v_mul_f32_e32 v45, v71, v0
	v_mul_f32_e32 v44, v72, v0
	v_mul_f32_e32 v45, v2, v45
	s_waitcnt lgkmcnt(0)
	s_nop 1
	v_add_f32_dpp v46, v46, v46 row_half_mirror row_mask:0xf bank_mask:0xf
	v_mul_f32_e32 v44, v3, v44
	v_cvt_pk_bf16_f32 v44, v45, v44
	v_mul_f32_e32 v45, v74, v0
	v_mul_f32_e32 v0, v73, v0
	v_mul_f32_e32 v45, v4, v45
	v_mul_f32_e32 v0, v5, v0
	v_cvt_pk_bf16_f32 v45, v45, v0
	s_waitcnt lgkmcnt(0)
	s_nop 1
	v_add_f32_dpp v0, v46, v46 row_mirror row_mask:0xf bank_mask:0xf
	v_add_co_u32_e32 v46, vcc, s9, v54
	v_fmamk_f32 v0, v0, 0x3c000000, v207
	s_nop 0
	v_addc_co_u32_e32 v47, vcc, 0, v55, vcc
	global_store_dwordx4 v[46:47], v[42:45], off
	v_rsq_f32_e32 v0, v0
	s_waitcnt vmcnt(10)
	v_lshlrev_b32_e32 v44, 16, v34
	s_waitcnt vmcnt(9)
	v_lshlrev_b32_e32 v45, 16, v38
	v_and_b32_e32 v34, 0xffff0000, v34
	v_and_b32_e32 v38, 0xffff0000, v38
	v_fma_f32 v44, -v56, v45, v44
	v_fma_f32 v45, -v56, v38, v34
	v_lshlrev_b32_e32 v34, 16, v35
	v_lshlrev_b32_e32 v38, 16, v39
	v_fma_f32 v46, -v56, v38, v34
	v_and_b32_e32 v34, 0xffff0000, v35
	v_and_b32_e32 v35, 0xffff0000, v39
	v_fma_f32 v47, -v56, v35, v34
	v_lshlrev_b32_e32 v34, 16, v36
	v_lshlrev_b32_e32 v35, 16, v40
	v_fma_f32 v50, -v56, v35, v34
	v_and_b32_e32 v34, 0xffff0000, v36
	v_and_b32_e32 v35, 0xffff0000, v40
	v_fma_f32 v40, -v56, v35, v34
	v_lshlrev_b32_e32 v34, 16, v37
	v_lshlrev_b32_e32 v35, 16, v41
	v_fma_f32 v51, -v56, v35, v34
	v_and_b32_e32 v34, 0xffff0000, v37
	v_and_b32_e32 v35, 0xffff0000, v41
	v_fma_f32 v41, -v56, v35, v34
	v_mul_f32_e32 v35, v45, v45
	v_fmac_f32_e32 v35, v44, v44
	v_fmac_f32_e32 v35, v46, v46
	v_fmac_f32_e32 v35, v47, v47
	v_fmac_f32_e32 v35, v50, v50
	v_fmac_f32_e32 v35, v40, v40
	v_fmac_f32_e32 v35, v51, v51
	v_fmac_f32_e32 v35, v41, v41
	v_mul_f32_e32 v0, v219, v0
	v_mul_f32_e32 v38, v62, v0
	v_mul_f32_e32 v37, v61, v0
	v_mul_f32_e32 v42, v52, v0
	s_waitcnt lgkmcnt(0)
	s_nop 1
	v_add_f32_dpp v36, v35, v35 quad_perm:[1,0,3,2] row_mask:0xf bank_mask:0xf
	v_mul_f32_e32 v35, v9, v38
	v_mul_f32_e32 v43, v53, v0
	v_mul_f32_e32 v37, v8, v37
	v_mul_f32_e32 v42, v6, v42
	s_waitcnt lgkmcnt(0)
	s_nop 1
	v_add_f32_dpp v38, v36, v36 quad_perm:[2,3,0,1] row_mask:0xf bank_mask:0xf
	v_mul_f32_e32 v43, v7, v43
	v_cvt_pk_bf16_f32 v34, v42, v43
	v_cvt_pk_bf16_f32 v35, v37, v35
	v_mul_f32_e32 v37, v63, v0
	s_waitcnt lgkmcnt(0)
	s_nop 1
	v_add_f32_dpp v38, v38, v38 row_half_mirror row_mask:0xf bank_mask:0xf
	v_mul_f32_e32 v36, v48, v0
	v_mul_f32_e32 v37, v2, v37
	v_mul_f32_e32 v36, v3, v36
	v_cvt_pk_bf16_f32 v36, v37, v36
	v_mul_f32_e32 v37, v64, v0
	v_mul_f32_e32 v0, v49, v0
	v_mul_f32_e32 v37, v4, v37
	v_mul_f32_e32 v0, v5, v0
	v_cvt_pk_bf16_f32 v37, v37, v0
	s_waitcnt lgkmcnt(0)
	s_nop 1
	v_add_f32_dpp v0, v38, v38 row_mirror row_mask:0xf bank_mask:0xf
	v_add_co_u32_e32 v38, vcc, s12, v54
	v_fmamk_f32 v0, v0, 0x3c000000, v207
	s_nop 0
	v_addc_co_u32_e32 v39, vcc, 0, v55, vcc
	global_store_dwordx4 v[38:39], v[34:37], off
	v_rsq_f32_e32 v0, v0
	s_waitcnt vmcnt(9)
	v_lshlrev_b32_e32 v36, 16, v26
	s_waitcnt vmcnt(8)
	v_lshlrev_b32_e32 v37, 16, v30
	v_and_b32_e32 v26, 0xffff0000, v26
	v_and_b32_e32 v30, 0xffff0000, v30
	v_fma_f32 v36, -v56, v37, v36
	v_fma_f32 v37, -v56, v30, v26
	v_lshlrev_b32_e32 v26, 16, v27
	v_lshlrev_b32_e32 v30, 16, v31
	v_fma_f32 v38, -v56, v30, v26
	v_and_b32_e32 v26, 0xffff0000, v27
	v_and_b32_e32 v27, 0xffff0000, v31
	v_fma_f32 v39, -v56, v27, v26
	v_lshlrev_b32_e32 v26, 16, v28
	v_lshlrev_b32_e32 v27, 16, v32
	v_fma_f32 v42, -v56, v27, v26
	v_and_b32_e32 v26, 0xffff0000, v28
	v_and_b32_e32 v27, 0xffff0000, v32
	v_fma_f32 v32, -v56, v27, v26
	v_lshlrev_b32_e32 v26, 16, v29
	v_lshlrev_b32_e32 v27, 16, v33
	v_fma_f32 v43, -v56, v27, v26
	v_and_b32_e32 v26, 0xffff0000, v29
	v_and_b32_e32 v27, 0xffff0000, v33
	v_fma_f32 v33, -v56, v27, v26
	v_mul_f32_e32 v27, v37, v37
	v_fmac_f32_e32 v27, v36, v36
	v_fmac_f32_e32 v27, v38, v38
	v_fmac_f32_e32 v27, v39, v39
	v_fmac_f32_e32 v27, v42, v42
	v_fmac_f32_e32 v27, v32, v32
	v_fmac_f32_e32 v27, v43, v43
	v_fmac_f32_e32 v27, v33, v33
	v_mul_f32_e32 v0, v219, v0
	v_mul_f32_e32 v30, v47, v0
	v_mul_f32_e32 v29, v46, v0
	v_mul_f32_e32 v34, v44, v0
	s_waitcnt lgkmcnt(0)
	s_nop 1
	v_add_f32_dpp v28, v27, v27 quad_perm:[1,0,3,2] row_mask:0xf bank_mask:0xf
	v_mul_f32_e32 v27, v9, v30
	v_mul_f32_e32 v35, v45, v0
	v_mul_f32_e32 v29, v8, v29
	v_mul_f32_e32 v34, v6, v34
	s_waitcnt lgkmcnt(0)
	s_nop 1
	v_add_f32_dpp v30, v28, v28 quad_perm:[2,3,0,1] row_mask:0xf bank_mask:0xf
	v_mul_f32_e32 v35, v7, v35
	v_cvt_pk_bf16_f32 v26, v34, v35
	v_cvt_pk_bf16_f32 v27, v29, v27
	v_mul_f32_e32 v29, v50, v0
	s_waitcnt lgkmcnt(0)
	s_nop 1
	v_add_f32_dpp v30, v30, v30 row_half_mirror row_mask:0xf bank_mask:0xf
	v_mul_f32_e32 v28, v40, v0
	v_mul_f32_e32 v29, v2, v29
	v_mul_f32_e32 v28, v3, v28
	v_cvt_pk_bf16_f32 v28, v29, v28
	v_mul_f32_e32 v29, v51, v0
	v_mul_f32_e32 v0, v41, v0
	v_mul_f32_e32 v29, v4, v29
	v_mul_f32_e32 v0, v5, v0
	v_cvt_pk_bf16_f32 v29, v29, v0
	s_waitcnt lgkmcnt(0)
; __device__ __forceinline__ float bf_lo(unsigned w) { return __uint_as_float(w << 16); }
; __device__ __forceinline__ float bf_hi(unsigned w) { return __uint_as_float(w & 0xffff0000u); }
; __device__ __forceinline__ unsigned pk2(float lo, float hi) { return pg8::cvt_pk_bf16(lo, hi); }
; __global__ void __launch_bounds__(NWAVES * 64, 2) trunk_fwd(Args args) {
;     ...
;                       for (int it = 0; it < 8; ++it) { const size_t row = rowbase + it * 4; const v4u a = aa[it], c = cc[it];
;                         float v[8] = {bf_lo(a.x) - lam * bf_lo(c.x), bf_hi(a.x) - lam * bf_hi(c.x), bf_lo(a.y) - lam * bf_lo(c.y), bf_hi(a.y) - lam * bf_hi(c.y),
;                                       bf_lo(a.z) - lam * bf_lo(c.z), bf_hi(a.z) - lam * bf_hi(c.z), bf_lo(a.w) - lam * bf_lo(c.w), bf_hi(a.w) - lam * bf_hi(c.w)};
;                         float sv = 0.f;
; #pragma unroll
;                         for (int e = 0; e < 8; ++e) sv += v[e] * v[e];
;                         sv += __shfl_xor(sv, 1); sv += __shfl_xor(sv, 2); sv += __shfl_xor(sv, 4); sv += __shfl_xor(sv, 8);
;                         const float r = __builtin_amdgcn_rsqf(sv * (1.0f / 128.0f) + EPS) * post;
;                         v4u o; o.x = pk2(v[0] * r * ga[0], v[1] * r * ga[1]); o.y = pk2(v[2] * r * ga[2], v[3] * r * ga[3]); o.z = pk2(v[4] * r * gb[0], v[5] * r * gb[1]); o.w = pk2(v[6] * r * gb[2], v[7] * r * gb[3]);
;                         *(v4u*)(MIX + row * 1024 + cofs) = o; }
	s_nop 1
	v_add_f32_dpp v0, v30, v30 row_mirror row_mask:0xf bank_mask:0xf
	v_add_co_u32_e32 v30, vcc, s20, v54
	v_fmamk_f32 v0, v0, 0x3c000000, v207
	s_nop 0
	v_addc_co_u32_e32 v31, vcc, 0, v55, vcc
	global_store_dwordx4 v[30:31], v[26:29], off
	v_rsq_f32_e32 v0, v0
	s_waitcnt vmcnt(8)
	v_lshlrev_b32_e32 v28, 16, v18
	s_waitcnt vmcnt(7)
	v_lshlrev_b32_e32 v29, 16, v22
	v_and_b32_e32 v18, 0xffff0000, v18
	v_and_b32_e32 v22, 0xffff0000, v22
	v_fma_f32 v28, -v56, v29, v28
	v_fma_f32 v29, -v56, v22, v18
	v_lshlrev_b32_e32 v18, 16, v19
	v_lshlrev_b32_e32 v22, 16, v23
	v_fma_f32 v30, -v56, v22, v18
	v_and_b32_e32 v18, 0xffff0000, v19
	v_and_b32_e32 v19, 0xffff0000, v23
	v_fma_f32 v31, -v56, v19, v18
	v_lshlrev_b32_e32 v18, 16, v20
	v_lshlrev_b32_e32 v19, 16, v24
	v_fma_f32 v34, -v56, v19, v18
	v_and_b32_e32 v18, 0xffff0000, v20
	v_and_b32_e32 v19, 0xffff0000, v24
	v_fma_f32 v24, -v56, v19, v18
	v_lshlrev_b32_e32 v18, 16, v21
	v_lshlrev_b32_e32 v19, 16, v25
	v_fma_f32 v35, -v56, v19, v18
	v_and_b32_e32 v18, 0xffff0000, v21
	v_and_b32_e32 v19, 0xffff0000, v25
	v_fma_f32 v25, -v56, v19, v18
	v_mul_f32_e32 v19, v29, v29
	v_fmac_f32_e32 v19, v28, v28
	v_fmac_f32_e32 v19, v30, v30
	v_fmac_f32_e32 v19, v31, v31
	v_fmac_f32_e32 v19, v34, v34
	v_fmac_f32_e32 v19, v24, v24
	v_fmac_f32_e32 v19, v35, v35
	v_fmac_f32_e32 v19, v25, v25
	v_mul_f32_e32 v0, v219, v0
	v_mul_f32_e32 v22, v39, v0
	v_mul_f32_e32 v21, v38, v0
	v_mul_f32_e32 v26, v36, v0
	s_waitcnt lgkmcnt(0)
	s_nop 1
	v_add_f32_dpp v20, v19, v19 quad_perm:[1,0,3,2] row_mask:0xf bank_mask:0xf
	v_mul_f32_e32 v19, v9, v22
	v_mul_f32_e32 v27, v37, v0
	v_mul_f32_e32 v21, v8, v21
	v_mul_f32_e32 v26, v6, v26
	s_waitcnt lgkmcnt(0)
	s_nop 1
	v_add_f32_dpp v22, v20, v20 quad_perm:[2,3,0,1] row_mask:0xf bank_mask:0xf
	v_mul_f32_e32 v27, v7, v27
	v_cvt_pk_bf16_f32 v18, v26, v27
	v_cvt_pk_bf16_f32 v19, v21, v19
	v_mul_f32_e32 v21, v42, v0
	s_waitcnt lgkmcnt(0)
	s_nop 1
	v_add_f32_dpp v22, v22, v22 row_half_mirror row_mask:0xf bank_mask:0xf
	v_mul_f32_e32 v20, v32, v0
	v_mul_f32_e32 v21, v2, v21
	v_mul_f32_e32 v20, v3, v20
	v_cvt_pk_bf16_f32 v20, v21, v20
	v_mul_f32_e32 v21, v43, v0
	v_mul_f32_e32 v0, v33, v0
	v_mul_f32_e32 v21, v4, v21
	v_mul_f32_e32 v0, v5, v0
	v_cvt_pk_bf16_f32 v21, v21, v0
	s_waitcnt lgkmcnt(0)
	s_nop 1
	v_add_f32_dpp v0, v22, v22 row_mirror row_mask:0xf bank_mask:0xf
	v_add_co_u32_e32 v22, vcc, s26, v54
	v_fmamk_f32 v0, v0, 0x3c000000, v207
	s_nop 0
	v_addc_co_u32_e32 v23, vcc, 0, v55, vcc
	global_store_dwordx4 v[22:23], v[18:21], off
	v_rsq_f32_e32 v0, v0
	s_waitcnt vmcnt(7)
	v_lshlrev_b32_e32 v20, 16, v10
	s_waitcnt vmcnt(6)
	v_lshlrev_b32_e32 v21, 16, v14
	v_and_b32_e32 v10, 0xffff0000, v10
	v_and_b32_e32 v14, 0xffff0000, v14
	v_fma_f32 v20, -v56, v21, v20
	v_fma_f32 v21, -v56, v14, v10
	v_lshlrev_b32_e32 v10, 16, v11
	v_lshlrev_b32_e32 v14, 16, v15
	v_fma_f32 v22, -v56, v14, v10
	v_and_b32_e32 v10, 0xffff0000, v11
	v_and_b32_e32 v11, 0xffff0000, v15
	v_fma_f32 v23, -v56, v11, v10
	v_lshlrev_b32_e32 v10, 16, v12
	v_lshlrev_b32_e32 v11, 16, v16
	v_fma_f32 v26, -v56, v11, v10
	v_and_b32_e32 v10, 0xffff0000, v12
	v_and_b32_e32 v11, 0xffff0000, v16
	v_fma_f32 v16, -v56, v11, v10
	v_lshlrev_b32_e32 v10, 16, v13
	v_lshlrev_b32_e32 v11, 16, v17
	v_fma_f32 v27, -v56, v11, v10
	v_and_b32_e32 v10, 0xffff0000, v13
	v_and_b32_e32 v11, 0xffff0000, v17
	v_fma_f32 v17, -v56, v11, v10
	v_mul_f32_e32 v11, v21, v21
	v_fmac_f32_e32 v11, v20, v20
	v_fmac_f32_e32 v11, v22, v22
	v_fmac_f32_e32 v11, v23, v23
	v_fmac_f32_e32 v11, v26, v26
	v_fmac_f32_e32 v11, v16, v16
	v_fmac_f32_e32 v11, v27, v27
	v_fmac_f32_e32 v11, v17, v17
	v_mul_f32_e32 v0, v219, v0
	v_mul_f32_e32 v14, v31, v0
	v_mul_f32_e32 v13, v30, v0
	v_mul_f32_e32 v18, v28, v0
	s_waitcnt lgkmcnt(0)
	s_nop 1
	v_add_f32_dpp v12, v11, v11 quad_perm:[1,0,3,2] row_mask:0xf bank_mask:0xf
	v_mul_f32_e32 v11, v9, v14
	v_mul_f32_e32 v19, v29, v0
	v_mul_f32_e32 v13, v8, v13
	v_mul_f32_e32 v18, v6, v18
	s_waitcnt lgkmcnt(0)
	s_nop 1
	v_add_f32_dpp v14, v12, v12 quad_perm:[2,3,0,1] row_mask:0xf bank_mask:0xf
	v_mul_f32_e32 v19, v7, v19
	v_cvt_pk_bf16_f32 v10, v18, v19
	v_cvt_pk_bf16_f32 v11, v13, v11
	v_mul_f32_e32 v13, v34, v0
	s_waitcnt lgkmcnt(0)
	s_nop 1
	v_add_f32_dpp v14, v14, v14 row_half_mirror row_mask:0xf bank_mask:0xf
	v_mul_f32_e32 v12, v24, v0
	v_mul_f32_e32 v13, v2, v13
	v_mul_f32_e32 v12, v3, v12
	v_cvt_pk_bf16_f32 v12, v13, v12
	v_mul_f32_e32 v13, v35, v0
	v_mul_f32_e32 v0, v25, v0
	v_mul_f32_e32 v13, v4, v13
	v_mul_f32_e32 v0, v5, v0
	v_cvt_pk_bf16_f32 v13, v13, v0
	s_waitcnt lgkmcnt(0)
	s_nop 1
	v_add_f32_dpp v0, v14, v14 row_mirror row_mask:0xf bank_mask:0xf
	v_fmamk_f32 v0, v0, 0x3c000000, v207
	v_rsq_f32_e32 v0, v0
	v_add_co_u32_e32 v14, vcc, s27, v54
	v_mul_f32_e32 v0, v219, v0
	s_nop 0
	v_addc_co_u32_e32 v15, vcc, 0, v55, vcc
	global_store_dwordx4 v[14:15], v[10:13], off
	s_nop 1
	v_mul_f32_e32 v10, v20, v0
	v_mul_f32_e32 v6, v6, v10
	v_mul_f32_e32 v10, v21, v0
	v_mul_f32_e32 v7, v7, v10
	v_cvt_pk_bf16_f32 v6, v6, v7
	v_mul_f32_e32 v7, v22, v0
	v_mul_f32_e32 v7, v8, v7
	v_mul_f32_e32 v8, v23, v0
	v_mul_f32_e32 v8, v9, v8
	v_cvt_pk_bf16_f32 v7, v7, v8
	v_mul_f32_e32 v8, v26, v0
	v_mul_f32_e32 v2, v2, v8
	v_mul_f32_e32 v8, v16, v0
	v_mul_f32_e32 v3, v3, v8
	v_cvt_pk_bf16_f32 v8, v2, v3
	v_mul_f32_e32 v2, v27, v0
	v_mul_f32_e32 v2, v4, v2
	v_mul_f32_e32 v0, v17, v0
	v_mul_f32_e32 v0, v5, v0
	v_cvt_pk_bf16_f32 v9, v2, v0
	v_add_co_u32_e32 v2, vcc, 0xe000, v54
	s_nop 1
	v_addc_co_u32_e32 v3, vcc, 0, v55, vcc
	global_store_dwordx4 v[2:3], v[6:9], off
	s_cbranch_scc1 .LBB0_357
